# attention v2 loop: kh=0 PV uses dst!=srcC MFMAs (no v_mov copies), PV lgkmcnt waits moved later, softmax/staging block interleaved into PV MFMA sequence per wave
# speedup vs baseline: 1.0004x; 1.0004x over previous
; #define SBAR() __builtin_amdgcn_sched_barrier(0)
; __device__ __forceinline__ void attn2_block(const Block2& B, char* lds) {
;     ...
;     float m_cur, mn_p, alpha_p = 1.f, pmax_own;
;     qkt_half<0>(p, K_lds, r32, hi, kh, qf, q0); SBAR(); A3_MASKMAX(0, 0);
;     __syncthreads();
;     m_cur = fmaxf(fmaxf(pmax_own, xm[(wid ^ 4) * 32 + r32]), -1e30f); mn_p = m_cur;
;     for (int t = 0; t < NT; t += 2) { A3_STEP(t, 0); A3_STEP(t + 1, 1); }
.LBB0_367:
	s_waitcnt lgkmcnt(0)
	s_barrier
	s_add_i32 s53, s53, -2
	s_add_i32 s87, s87, 2
	s_cmp_gt_u32 s88, s85
	s_cbranch_scc1 .LBB0_404

; template <int VB, bool SK>
; __device__ __forceinline__ void pv_tile(f32x16* o, int vb0, bf16x8 pa0, bf16x8 pa1, bf16x8 pa2, bf16x8 pa3, bool act) {
;     if (SK && !act) return;
;     ...
;     PV_D0(0); PV_D0(1); PV_D0(2); PV_D0(3);
.LBB0_369:
	ds_read_b128 v[184:187], v220 offset:16384
	ds_read_b128 v[180:183], v220 offset:17408
	ds_read_b128 v[64:67], v211
	ds_read_b128 v[68:71], v211 offset:128
	s_waitcnt lgkmcnt(1)
	v_mfma_f32_32x32x16_bf16 v[128:143], v[64:67], v[144:147], 0
	ds_read_b128 v[64:67], v212
	ds_read_b128 v[72:75], v210
	ds_read_b128 v[76:79], v210 offset:1024
	ds_read_b128 v[80:83], v212 offset:128
	s_waitcnt lgkmcnt(2)
	v_mfma_f32_32x32x16_bf16 v[128:143], v[64:67], v[72:75], v[128:143]
	ds_read_b128 v[64:67], v213
	ds_read_b128 v[72:75], v213 offset:128
	s_waitcnt lgkmcnt(1)
	v_mfma_f32_32x32x16_bf16 v[128:143], v[64:67], v[76:79], v[128:143]
	ds_read_b128 v[64:67], v214
	ds_read_b128 v[76:79], v210 offset:2048
	ds_read_b128 v[84:87], v210 offset:3072
	ds_read_b128 v[88:91], v214 offset:128
	s_waitcnt lgkmcnt(2)
	v_mfma_f32_32x32x16_bf16 v[128:143], v[64:67], v[76:79], v[128:143]
	s_waitcnt lgkmcnt(1)
	v_mfma_f32_32x32x16_bf16 v[128:143], v[68:71], v[84:87], v[128:143]
	ds_read_b128 v[64:67], v210 offset:4096
	ds_read_b128 v[68:71], v210 offset:5120
	s_waitcnt lgkmcnt(1)
	v_mfma_f32_32x32x16_bf16 v[128:143], v[80:83], v[64:67], v[128:143]
	ds_read_b128 v[64:67], v210 offset:6144
	s_waitcnt lgkmcnt(1)
	v_mfma_f32_32x32x16_bf16 v[128:143], v[72:75], v[68:71], v[128:143]
	s_waitcnt lgkmcnt(0)
	v_mfma_f32_32x32x16_bf16 v[128:143], v[88:91], v[64:67], v[128:143]
	s_mov_b64 s[4:5], -1
	s_and_b64 vcc, exec, s[48:49]
	s_cbranch_vccz .LBB0_371
	ds_read_b64_tr_b16 v[80:81], v194 offset:0xc000
	ds_read_b64_tr_b16 v[82:83], v194 offset:0xc800
	ds_read_b64_tr_b16 v[84:85], v194 offset:0xd000
	ds_read_b64_tr_b16 v[86:87], v194 offset:0xd800
	ds_read_b64_tr_b16 v[88:89], v194 offset:0xe000
	ds_read_b64_tr_b16 v[90:91], v194 offset:0xe800
	ds_read_b64_tr_b16 v[92:93], v194 offset:0xf000
	ds_read_b64_tr_b16 v[94:95], v194 offset:0xf800
	s_waitcnt lgkmcnt(0)
	s_nop 0
	v_mfma_f32_32x32x16_bf16 v[64:79], v[184:187], v[80:83], v[0:15]
	ds_read_b64_tr_b16 v[96:97], v194 offset:0xc200
	ds_read_b64_tr_b16 v[98:99], v194 offset:0xca00
	ds_read_b64_tr_b16 v[100:101], v194 offset:0xd200
	ds_read_b64_tr_b16 v[102:103], v194 offset:0xda00
	ds_read_b64_tr_b16 v[104:105], v194 offset:0xe200
	ds_read_b64_tr_b16 v[106:107], v194 offset:0xea00
	ds_read_b64_tr_b16 v[108:109], v194 offset:0xf200
	v_mfma_f32_32x32x16_bf16 v[64:79], v[180:183], v[84:87], v[64:79]
	ds_read_b64_tr_b16 v[110:111], v194 offset:0xfa00
	v_mfma_f32_32x32x16_bf16 v[64:79], v[172:175], v[88:91], v[64:79]
	v_mfma_f32_32x32x16_bf16 v[64:79], v[176:179], v[92:95], v[64:79]
	s_waitcnt lgkmcnt(0)
	v_mfma_f32_32x32x16_bf16 v[80:95], v[184:187], v[96:99], v[16:31]
	ds_read_b64_tr_b16 v[112:113], v194 offset:0xc400
	ds_read_b64_tr_b16 v[114:115], v194 offset:0xcc00
	ds_read_b64_tr_b16 v[116:117], v194 offset:0xd400
	ds_read_b64_tr_b16 v[118:119], v194 offset:0xdc00
	ds_read_b64_tr_b16 v[120:121], v194 offset:0xe400
	ds_read_b64_tr_b16 v[122:123], v194 offset:0xec00
	ds_read_b64_tr_b16 v[124:125], v194 offset:0xf400
	v_mfma_f32_32x32x16_bf16 v[80:95], v[180:183], v[100:103], v[80:95]
	ds_read_b64_tr_b16 v[126:127], v194 offset:0xfc00
	s_add_i32 s38, s87, -3
	s_add_i32 s50, s53, 1
	s_and_b64 s[4:5], s[46:47], exec
	s_cselect_b32 s4, s38, s50
	s_lshl_b32 s4, s4, 6
	s_cmp_le_i32 s4, s86
	s_cselect_b64 vcc, -1, 0
	v_cndmask_b32_e32 v14, v204, v130, vcc
	v_cndmask_b32_e32 v13, v204, v131, vcc
	v_cndmask_b32_e32 v10, v204, v134, vcc
	v_cndmask_b32_e32 v9, v204, v135, vcc
	v_max_f32_e32 v0, v13, v13
	v_max_f32_e32 v17, v14, v14
	v_cndmask_b32_e32 v8, v204, v136, vcc
	v_cndmask_b32_e32 v7, v204, v137, vcc
	v_max_f32_e32 v0, v17, v0
	v_max_f32_e32 v17, v9, v9
	v_max_f32_e32 v18, v10, v10
	v_cndmask_b32_e32 v6, v204, v138, vcc
	v_mfma_f32_32x32x16_bf16 v[80:95], v[172:175], v[104:107], v[80:95]
	v_cndmask_b32_e32 v5, v204, v139, vcc
	v_max_f32_e32 v17, v18, v17
	v_max_f32_e32 v18, v7, v7
	v_max_f32_e32 v19, v8, v8
	v_cndmask_b32_e32 v2, v204, v142, vcc
	v_cndmask_b32_e32 v1, v204, v143, vcc
	v_max_f32_e32 v18, v19, v18
	v_max_f32_e32 v19, v5, v5
	v_max_f32_e32 v20, v6, v6
	v_max_f32_e32 v19, v20, v19
	v_max_f32_e32 v20, v1, v1
	v_max_f32_e32 v21, v2, v2
	v_cndmask_b32_e32 v4, v204, v140, vcc
	v_cndmask_b32_e32 v3, v204, v141, vcc
	v_max_f32_e32 v20, v21, v20
	v_mfma_f32_32x32x16_bf16 v[80:95], v[176:179], v[108:111], v[80:95]
	v_cndmask_b32_e32 v12, v204, v132, vcc
	v_cndmask_b32_e32 v11, v204, v133, vcc
	v_cndmask_b32_e32 v16, v204, v128, vcc
	v_cndmask_b32_e32 v15, v204, v129, vcc
	v_max3_f32 v20, v4, v3, v20
	v_max3_f32 v0, v16, v15, v0
	v_max3_f32 v17, v12, v11, v17
	v_max3_f32 v18, v18, v19, v20
	v_max3_f32 v0, v0, v17, v18
	v_mov_b32_e32 v17, v0
	s_nop 1
	v_permlane32_swap_b32_e32 v0, v17
	v_max_f32_e32 v17, v17, v17
	v_max_f32_e32 v0, v0, v0
	v_max_f32_e32 v0, v0, v17
	s_waitcnt lgkmcnt(0)
	v_mfma_f32_32x32x16_bf16 v[96:111], v[184:187], v[112:115], v[32:47]
	ds_read_b64_tr_b16 v[230:231], v194 offset:0xc600
	ds_read_b64_tr_b16 v[232:233], v194 offset:0xce00
	ds_read_b64_tr_b16 v[234:235], v194 offset:0xd600
	ds_read_b64_tr_b16 v[236:237], v194 offset:0xde00
	ds_read_b64_tr_b16 v[238:239], v194 offset:0xe600
	ds_read_b64_tr_b16 v[240:241], v194 offset:0xee00
	ds_read_b64_tr_b16 v[242:243], v194 offset:0xf600
	s_and_saveexec_b64 s[4:5], s[2:3]
	ds_write_b32 v226, v0
	s_or_b64 exec, exec, s[4:5]
	s_cmp_le_u32 s38, s84
	s_cselect_b64 s[4:5], -1, 0
	s_cmp_gt_u32 s38, s84
	s_cbranch_scc1 .Lm0_h1B_381
	s_waitcnt vmcnt(1)
	ds_write_b128 v215, v[148:151]
	s_waitcnt vmcnt(0)
	ds_write_b128 v215, v[152:155] offset:8192
; template <int VB, bool SK>
; __device__ __forceinline__ void pv_tile(f32x16* o, int vb0, bf16x8 pa0, bf16x8 pa1, bf16x8 pa2, bf16x8 pa3, bool act) {
;     if (SK && !act) return;
;     ...
;     PV_D0(0); PV_D0(1); PV_D0(2); PV_D0(3);
.Lm0_h1B_381:
	v_mfma_f32_32x32x16_bf16 v[96:111], v[180:183], v[116:119], v[96:111]
	ds_read_b64_tr_b16 v[244:245], v194 offset:0xfe00
	s_waitcnt vmcnt(3)
	ds_write_b128 v216, v[156:159]
	s_waitcnt vmcnt(2)
	ds_write_b128 v217, v[160:163]
	s_waitcnt vmcnt(1)
	ds_write_b128 v216, v[164:167] offset:16384
	s_waitcnt vmcnt(0)
	ds_write_b128 v217, v[168:171] offset:16384
	v_mfma_f32_32x32x16_bf16 v[96:111], v[172:175], v[120:123], v[96:111]
	s_add_i32 s88, s87, -1
	s_cmp_le_u32 s88, s85
	s_cselect_b64 s[50:51], -1, 0
	s_cmp_gt_u32 s88, s85
	s_cbranch_scc1 .Lm0_h1B_383
	s_add_i32 s38, s53, -1
	s_and_b64 s[90:91], s[46:47], exec
	s_cselect_b32 s38, s88, s38
	s_lshl_b32 s38, s38, 6
	s_lshl_b64 s[90:91], s[38:39], 8
	s_or_b32 s38, s38, 32
	v_lshl_add_u64 v[18:19], v[198:199], 0, s[90:91]
	s_lshl_b64 s[90:91], s[38:39], 8
	v_lshl_add_u64 v[20:21], v[198:199], 0, s[90:91]
	global_load_dwordx4 v[148:151], v[18:19], off
	global_load_dwordx4 v[152:155], v[20:21], off
.Lm0_h1B_383:
	v_mfma_f32_32x32x16_bf16 v[96:111], v[176:179], v[124:127], v[96:111]
	s_andn2_b64 vcc, exec, s[4:5]
	s_add_i32 s89, s87, -2
	s_cbranch_vccnz .Lm0_h1B_385
	s_and_b64 s[4:5], s[46:47], exec
	s_cselect_b32 s4, s89, s53
	s_lshl_b32 s38, s4, 6
	s_lshl_b64 s[4:5], s[38:39], 8
	s_or_b32 s38, s38, 32
	v_lshl_add_u64 v[18:19], v[200:201], 0, s[4:5]
	s_lshl_b64 s[90:91], s[38:39], 8
	v_lshl_add_u64 v[20:21], v[200:201], 0, s[90:91]
	global_load_dwordx4 v[156:159], v[18:19], off
	global_load_dwordx4 v[160:163], v[20:21], off
	v_lshl_add_u64 v[18:19], v[202:203], 0, s[4:5]
	v_lshl_add_u64 v[20:21], v[202:203], 0, s[90:91]
	global_load_dwordx4 v[164:167], v[18:19], off
	global_load_dwordx4 v[168:171], v[20:21], off
.Lm0_h1B_385:
	s_waitcnt lgkmcnt(0)
	v_mfma_f32_32x32x16_bf16 v[112:127], v[184:187], v[230:233], v[48:63]
	v_mul_f32_e32 v17, 0xbe0293ee, v218
	v_fmamk_f32 v16, v16, 0x3e0293ee, v17
	v_fmamk_f32 v15, v15, 0x3e0293ee, v17
	v_fmamk_f32 v14, v14, 0x3e0293ee, v17
	v_fmamk_f32 v13, v13, 0x3e0293ee, v17
	v_exp_f32_e32 v16, v16
	v_exp_f32_e32 v15, v15
	v_exp_f32_e32 v14, v14
	v_exp_f32_e32 v13, v13
	v_mfma_f32_32x32x16_bf16 v[112:127], v[180:183], v[234:237], v[112:127]
	v_fmamk_f32 v12, v12, 0x3e0293ee, v17
	v_fmamk_f32 v11, v11, 0x3e0293ee, v17
	v_fmamk_f32 v10, v10, 0x3e0293ee, v17
	v_fmamk_f32 v9, v9, 0x3e0293ee, v17
	v_exp_f32_e32 v12, v12
	v_exp_f32_e32 v11, v11
	v_exp_f32_e32 v10, v10
	v_exp_f32_e32 v9, v9
	v_mfma_f32_32x32x16_bf16 v[112:127], v[172:175], v[238:241], v[112:127]
	v_fmamk_f32 v8, v8, 0x3e0293ee, v17
	v_fmamk_f32 v7, v7, 0x3e0293ee, v17
	v_fmamk_f32 v6, v6, 0x3e0293ee, v17
	v_fmamk_f32 v5, v5, 0x3e0293ee, v17
	v_exp_f32_e32 v8, v8
	v_exp_f32_e32 v7, v7
	v_exp_f32_e32 v6, v6
	v_exp_f32_e32 v5, v5
	v_mfma_f32_32x32x16_bf16 v[112:127], v[176:179], v[242:245], v[112:127]
	v_fmamk_f32 v4, v4, 0x3e0293ee, v17
	v_fmamk_f32 v3, v3, 0x3e0293ee, v17
	v_fmamk_f32 v2, v2, 0x3e0293ee, v17
	v_fmac_f32_e32 v17, 0x3e0293ee, v1
	v_exp_f32_e32 v4, v4
	v_exp_f32_e32 v3, v3
	v_exp_f32_e32 v2, v2
	v_exp_f32_e32 v1, v17
	v_add_f32_e32 v17, v16, v15
	v_add_f32_e32 v18, v14, v13
	v_add_f32_e32 v17, v17, v18
	v_add_f32_e32 v18, v12, v11
	v_add_f32_e32 v19, v10, v9
	v_add_f32_e32 v18, v18, v19
	v_add_f32_e32 v17, v17, v18
	v_add_f32_e32 v18, v8, v7
	v_add_f32_e32 v19, v6, v5
	v_add_f32_e32 v18, v18, v19
	v_add_f32_e32 v19, v4, v3
	v_add_f32_e32 v20, v2, v1
	v_add_f32_e32 v19, v19, v20
	v_add_f32_e32 v18, v18, v19
	v_add_f32_e32 v231, v17, v18
	v_mov_b32_e32 v232, v231
	s_nop 1
	v_permlane32_swap_b32_e32 v231, v232
	v_cvt_pk_bf16_f32 v172, v16, v15
	v_cvt_pk_bf16_f32 v173, v14, v13
	v_cvt_pk_bf16_f32 v174, v12, v11
	v_cvt_pk_bf16_f32 v175, v10, v9
	v_cvt_pk_bf16_f32 v176, v8, v7
	v_cvt_pk_bf16_f32 v177, v6, v5
	v_cvt_pk_bf16_f32 v178, v4, v3
	v_cvt_pk_bf16_f32 v179, v2, v1
	s_nop 0
	v_permlane32_swap_b32_e32 v172, v174
	v_permlane32_swap_b32_e32 v173, v175
	v_permlane32_swap_b32_e32 v176, v178
	v_permlane32_swap_b32_e32 v177, v179
	ds_write_b128 v219, v[172:175]
	ds_write_b128 v219, v[176:179] offset:1024
	s_mov_b64 s[4:5], 0
.LBB0_371:
	s_andn2_b64 vcc, exec, s[4:5]
	s_cbranch_vccnz .LBB0_373
	ds_read_b64_tr_b16 v[80:81], v194 offset:0x8000
	ds_read_b64_tr_b16 v[82:83], v194 offset:0x8800
	ds_read_b64_tr_b16 v[84:85], v194 offset:0x9000
	ds_read_b64_tr_b16 v[86:87], v194 offset:0x9800
	ds_read_b64_tr_b16 v[88:89], v194 offset:0xa000
	ds_read_b64_tr_b16 v[90:91], v194 offset:0xa800
	ds_read_b64_tr_b16 v[92:93], v194 offset:0xb000
	ds_read_b64_tr_b16 v[94:95], v194 offset:0xb800
	s_waitcnt lgkmcnt(0)
	s_nop 0
	v_mfma_f32_32x32x16_bf16 v[64:79], v[172:175], v[80:83], v[0:15]
	ds_read_b64_tr_b16 v[96:97], v194 offset:0x8200
	ds_read_b64_tr_b16 v[98:99], v194 offset:0x8a00
	ds_read_b64_tr_b16 v[100:101], v194 offset:0x9200
	ds_read_b64_tr_b16 v[102:103], v194 offset:0x9a00
	ds_read_b64_tr_b16 v[104:105], v194 offset:0xa200
	ds_read_b64_tr_b16 v[106:107], v194 offset:0xaa00
	ds_read_b64_tr_b16 v[108:109], v194 offset:0xb200
	v_mfma_f32_32x32x16_bf16 v[64:79], v[176:179], v[84:87], v[64:79]
	ds_read_b64_tr_b16 v[110:111], v194 offset:0xba00
	v_mfma_f32_32x32x16_bf16 v[64:79], v[184:187], v[88:91], v[64:79]
	v_mfma_f32_32x32x16_bf16 v[64:79], v[180:183], v[92:95], v[64:79]
	s_waitcnt lgkmcnt(0)
; template <int VB, bool SK>
; __device__ __forceinline__ void pv_tile(f32x16* o, int vb0, bf16x8 pa0, bf16x8 pa1, bf16x8 pa2, bf16x8 pa3, bool act) {
;     if (SK && !act) return;
;     ...
;     PV_D0(0); PV_D0(1); PV_D0(2); PV_D0(3);
	v_mfma_f32_32x32x16_bf16 v[80:95], v[172:175], v[96:99], v[16:31]
	ds_read_b64_tr_b16 v[112:113], v194 offset:0x8400
	ds_read_b64_tr_b16 v[114:115], v194 offset:0x8c00
	ds_read_b64_tr_b16 v[116:117], v194 offset:0x9400
	ds_read_b64_tr_b16 v[118:119], v194 offset:0x9c00
	ds_read_b64_tr_b16 v[120:121], v194 offset:0xa400
	ds_read_b64_tr_b16 v[122:123], v194 offset:0xac00
	ds_read_b64_tr_b16 v[124:125], v194 offset:0xb400
	v_mfma_f32_32x32x16_bf16 v[80:95], v[176:179], v[100:103], v[80:95]
	ds_read_b64_tr_b16 v[126:127], v194 offset:0xbc00
	s_add_i32 s38, s87, -3
	s_add_i32 s50, s53, 1
	s_and_b64 s[4:5], s[46:47], exec
	s_cselect_b32 s4, s38, s50
	s_lshl_b32 s4, s4, 6
	s_cmp_le_i32 s4, s86
	s_cselect_b64 vcc, -1, 0
	v_cndmask_b32_e32 v14, v204, v130, vcc
	v_cndmask_b32_e32 v13, v204, v131, vcc
	v_cndmask_b32_e32 v10, v204, v134, vcc
	v_cndmask_b32_e32 v9, v204, v135, vcc
	v_max_f32_e32 v0, v13, v13
	v_max_f32_e32 v17, v14, v14
	v_cndmask_b32_e32 v8, v204, v136, vcc
	v_cndmask_b32_e32 v7, v204, v137, vcc
	v_max_f32_e32 v0, v17, v0
	v_max_f32_e32 v17, v9, v9
	v_max_f32_e32 v18, v10, v10
	v_cndmask_b32_e32 v6, v204, v138, vcc
	v_mfma_f32_32x32x16_bf16 v[80:95], v[184:187], v[104:107], v[80:95]
	v_cndmask_b32_e32 v5, v204, v139, vcc
	v_max_f32_e32 v17, v18, v17
	v_max_f32_e32 v18, v7, v7
	v_max_f32_e32 v19, v8, v8
	v_cndmask_b32_e32 v2, v204, v142, vcc
	v_cndmask_b32_e32 v1, v204, v143, vcc
	v_max_f32_e32 v18, v19, v18
	v_max_f32_e32 v19, v5, v5
	v_max_f32_e32 v20, v6, v6
	v_max_f32_e32 v19, v20, v19
	v_max_f32_e32 v20, v1, v1
	v_max_f32_e32 v21, v2, v2
	v_cndmask_b32_e32 v4, v204, v140, vcc
	v_cndmask_b32_e32 v3, v204, v141, vcc
	v_max_f32_e32 v20, v21, v20
	v_mfma_f32_32x32x16_bf16 v[80:95], v[180:183], v[108:111], v[80:95]
	v_cndmask_b32_e32 v12, v204, v132, vcc
	v_cndmask_b32_e32 v11, v204, v133, vcc
	v_cndmask_b32_e32 v16, v204, v128, vcc
	v_cndmask_b32_e32 v15, v204, v129, vcc
	v_max3_f32 v20, v4, v3, v20
	v_max3_f32 v0, v16, v15, v0
	v_max3_f32 v17, v12, v11, v17
	v_max3_f32 v18, v18, v19, v20
	v_max3_f32 v0, v0, v17, v18
	v_mov_b32_e32 v17, v0
	s_nop 1
	v_permlane32_swap_b32_e32 v0, v17
	v_max_f32_e32 v17, v17, v17
	v_max_f32_e32 v0, v0, v0
	v_max_f32_e32 v0, v0, v17
	s_waitcnt lgkmcnt(0)
	v_mfma_f32_32x32x16_bf16 v[96:111], v[172:175], v[112:115], v[32:47]
	ds_read_b64_tr_b16 v[230:231], v194 offset:0x8600
	ds_read_b64_tr_b16 v[232:233], v194 offset:0x8e00
	ds_read_b64_tr_b16 v[234:235], v194 offset:0x9600
	ds_read_b64_tr_b16 v[236:237], v194 offset:0x9e00
	ds_read_b64_tr_b16 v[238:239], v194 offset:0xa600
	ds_read_b64_tr_b16 v[240:241], v194 offset:0xae00
	ds_read_b64_tr_b16 v[242:243], v194 offset:0xb600
	s_and_saveexec_b64 s[4:5], s[2:3]
	ds_write_b32 v226, v0
	s_or_b64 exec, exec, s[4:5]
	s_cmp_le_u32 s38, s84
	s_cselect_b64 s[4:5], -1, 0
	s_cmp_gt_u32 s38, s84
	s_cbranch_scc1 .Lm0_h1A_381
	s_waitcnt vmcnt(1)
	ds_write_b128 v215, v[148:151]
	s_waitcnt vmcnt(0)
	ds_write_b128 v215, v[152:155] offset:8192
.Lm0_h1A_381:
	v_mfma_f32_32x32x16_bf16 v[96:111], v[176:179], v[116:119], v[96:111]
	ds_read_b64_tr_b16 v[244:245], v194 offset:0xbe00
	s_waitcnt vmcnt(3)
	ds_write_b128 v216, v[156:159]
	s_waitcnt vmcnt(2)
	ds_write_b128 v217, v[160:163]
	s_waitcnt vmcnt(1)
	ds_write_b128 v216, v[164:167] offset:16384
	s_waitcnt vmcnt(0)
	ds_write_b128 v217, v[168:171] offset:16384
	v_mfma_f32_32x32x16_bf16 v[96:111], v[184:187], v[120:123], v[96:111]
	s_add_i32 s88, s87, -1
	s_cmp_le_u32 s88, s85
	s_cselect_b64 s[50:51], -1, 0
	s_cmp_gt_u32 s88, s85
	s_cbranch_scc1 .Lm0_h1A_383
	s_add_i32 s38, s53, -1
	s_and_b64 s[90:91], s[46:47], exec
	s_cselect_b32 s38, s88, s38
	s_lshl_b32 s38, s38, 6
	s_lshl_b64 s[90:91], s[38:39], 8
	s_or_b32 s38, s38, 32
	v_lshl_add_u64 v[18:19], v[198:199], 0, s[90:91]
	s_lshl_b64 s[90:91], s[38:39], 8
	v_lshl_add_u64 v[20:21], v[198:199], 0, s[90:91]
	global_load_dwordx4 v[148:151], v[18:19], off
	global_load_dwordx4 v[152:155], v[20:21], off
.Lm0_h1A_383:
	v_mfma_f32_32x32x16_bf16 v[96:111], v[180:183], v[124:127], v[96:111]
	s_andn2_b64 vcc, exec, s[4:5]
	s_add_i32 s89, s87, -2
	s_cbranch_vccnz .Lm0_h1A_385
	s_and_b64 s[4:5], s[46:47], exec
	s_cselect_b32 s4, s89, s53
	s_lshl_b32 s38, s4, 6
	s_lshl_b64 s[4:5], s[38:39], 8
	s_or_b32 s38, s38, 32
	v_lshl_add_u64 v[18:19], v[200:201], 0, s[4:5]
	s_lshl_b64 s[90:91], s[38:39], 8
	v_lshl_add_u64 v[20:21], v[200:201], 0, s[90:91]
	global_load_dwordx4 v[156:159], v[18:19], off
	global_load_dwordx4 v[160:163], v[20:21], off
	v_lshl_add_u64 v[18:19], v[202:203], 0, s[4:5]
	v_lshl_add_u64 v[20:21], v[202:203], 0, s[90:91]
	global_load_dwordx4 v[164:167], v[18:19], off
	global_load_dwordx4 v[168:171], v[20:21], off
.Lm0_h1A_385:
	s_waitcnt lgkmcnt(0)
	v_mfma_f32_32x32x16_bf16 v[112:127], v[172:175], v[230:233], v[48:63]
	v_mul_f32_e32 v17, 0xbe0293ee, v218
	v_fmamk_f32 v16, v16, 0x3e0293ee, v17
	v_fmamk_f32 v15, v15, 0x3e0293ee, v17
	v_fmamk_f32 v14, v14, 0x3e0293ee, v17
	v_fmamk_f32 v13, v13, 0x3e0293ee, v17
	v_exp_f32_e32 v16, v16
	v_exp_f32_e32 v15, v15
	v_exp_f32_e32 v14, v14
	v_exp_f32_e32 v13, v13
	v_mfma_f32_32x32x16_bf16 v[112:127], v[176:179], v[234:237], v[112:127]
	v_fmamk_f32 v12, v12, 0x3e0293ee, v17
	v_fmamk_f32 v11, v11, 0x3e0293ee, v17
	v_fmamk_f32 v10, v10, 0x3e0293ee, v17
	v_fmamk_f32 v9, v9, 0x3e0293ee, v17
	v_exp_f32_e32 v12, v12
	v_exp_f32_e32 v11, v11
	v_exp_f32_e32 v10, v10
	v_exp_f32_e32 v9, v9
	v_mfma_f32_32x32x16_bf16 v[112:127], v[184:187], v[238:241], v[112:127]
	v_fmamk_f32 v8, v8, 0x3e0293ee, v17
	v_fmamk_f32 v7, v7, 0x3e0293ee, v17
	v_fmamk_f32 v6, v6, 0x3e0293ee, v17
	v_fmamk_f32 v5, v5, 0x3e0293ee, v17
	v_exp_f32_e32 v8, v8
	v_exp_f32_e32 v7, v7
	v_exp_f32_e32 v6, v6
	v_exp_f32_e32 v5, v5
	v_mfma_f32_32x32x16_bf16 v[112:127], v[180:183], v[242:245], v[112:127]
	v_fmamk_f32 v4, v4, 0x3e0293ee, v17
	v_fmamk_f32 v3, v3, 0x3e0293ee, v17
	v_fmamk_f32 v2, v2, 0x3e0293ee, v17
	v_fmac_f32_e32 v17, 0x3e0293ee, v1
	v_exp_f32_e32 v4, v4
	v_exp_f32_e32 v3, v3
	v_exp_f32_e32 v2, v2
	v_exp_f32_e32 v1, v17
	v_add_f32_e32 v17, v16, v15
	v_add_f32_e32 v18, v14, v13
	v_add_f32_e32 v17, v17, v18
	v_add_f32_e32 v18, v12, v11
	v_add_f32_e32 v19, v10, v9
	v_add_f32_e32 v18, v18, v19
	v_add_f32_e32 v17, v17, v18
	v_add_f32_e32 v18, v8, v7
	v_add_f32_e32 v19, v6, v5
	v_add_f32_e32 v18, v18, v19
	v_add_f32_e32 v19, v4, v3
	v_add_f32_e32 v20, v2, v1
	v_add_f32_e32 v19, v19, v20
	v_add_f32_e32 v18, v18, v19
	v_add_f32_e32 v231, v17, v18
	v_mov_b32_e32 v232, v231
	s_nop 1
	v_permlane32_swap_b32_e32 v231, v232
	v_cvt_pk_bf16_f32 v172, v16, v15
	v_cvt_pk_bf16_f32 v173, v14, v13
	v_cvt_pk_bf16_f32 v174, v12, v11
	v_cvt_pk_bf16_f32 v175, v10, v9
	v_cvt_pk_bf16_f32 v176, v8, v7
	v_cvt_pk_bf16_f32 v177, v6, v5
	v_cvt_pk_bf16_f32 v178, v4, v3
	v_cvt_pk_bf16_f32 v179, v2, v1
	s_nop 0
	v_permlane32_swap_b32_e32 v172, v174
	v_permlane32_swap_b32_e32 v173, v175
	v_permlane32_swap_b32_e32 v176, v178
	v_permlane32_swap_b32_e32 v177, v179
	ds_write_b128 v219, v[172:175]
	ds_write_b128 v219, v[176:179] offset:1024

; template <int VB, bool SK>
; __device__ __forceinline__ void pv_tile(f32x16* o, int vb0, bf16x8 pa0, bf16x8 pa1, bf16x8 pa2, bf16x8 pa3, bool act) {
;     if (SK && !act) return;
;     ...
;     PV_D0(0); PV_D0(1); PV_D0(2); PV_D0(3);
.LBB0_377:
	s_waitcnt lgkmcnt(0)
	s_barrier
	ds_read_b32 v1, v197
	v_max_f32_e32 v0, v0, v0
	v_mov_b32_e32 v230, 1.0
	s_waitcnt lgkmcnt(0)
	v_max_f32_e32 v1, v1, v1
	v_max_f32_e32 v0, v0, v1
	v_sub_f32_e32 v1, v0, v218
	v_mul_f32_e32 v1, 0x3db504f3, v1
	v_cmp_ge_f32_e32 vcc, s72, v1
	s_cmp_eq_u64 vcc, exec
	s_cbranch_scc0 .LBB0_403
.LBB0_386:
	ds_read_b128 v[184:187], v220
	ds_read_b128 v[180:183], v220 offset:1024
	ds_read_b128 v[0:3], v222
	ds_read_b128 v[4:7], v222 offset:128
	s_waitcnt lgkmcnt(1)
	v_mfma_f32_32x32x16_bf16 v[128:143], v[0:3], v[144:147], 0
	ds_read_b128 v[0:3], v223
	ds_read_b128 v[8:11], v210
	ds_read_b128 v[12:15], v210 offset:1024
	ds_read_b128 v[16:19], v223 offset:128
	s_waitcnt lgkmcnt(2)
	v_mfma_f32_32x32x16_bf16 v[128:143], v[0:3], v[8:11], v[128:143]
	ds_read_b128 v[0:3], v224
	ds_read_b128 v[8:11], v224 offset:128
	s_waitcnt lgkmcnt(1)
	v_mfma_f32_32x32x16_bf16 v[128:143], v[0:3], v[12:15], v[128:143]
	ds_read_b128 v[0:3], v225
	ds_read_b128 v[12:15], v210 offset:2048
	ds_read_b128 v[20:23], v210 offset:3072
	ds_read_b128 v[24:27], v225 offset:128
	s_waitcnt lgkmcnt(2)
	v_mfma_f32_32x32x16_bf16 v[128:143], v[0:3], v[12:15], v[128:143]
	s_waitcnt lgkmcnt(1)
	v_mfma_f32_32x32x16_bf16 v[128:143], v[4:7], v[20:23], v[128:143]
	ds_read_b128 v[0:3], v210 offset:4096
	ds_read_b128 v[4:7], v210 offset:5120
	s_waitcnt lgkmcnt(1)
	v_mfma_f32_32x32x16_bf16 v[128:143], v[16:19], v[0:3], v[128:143]
	ds_read_b128 v[0:3], v210 offset:6144
	s_waitcnt lgkmcnt(1)
	v_mfma_f32_32x32x16_bf16 v[128:143], v[8:11], v[4:7], v[128:143]
	s_waitcnt lgkmcnt(0)
	v_mfma_f32_32x32x16_bf16 v[128:143], v[24:27], v[0:3], v[128:143]
	s_mov_b64 s[4:5], -1
	s_and_b64 vcc, exec, s[48:49]
	s_cbranch_vccz .LBB0_388
	ds_read_b64_tr_b16 v[16:17], v194 offset:0x4000
	ds_read_b64_tr_b16 v[18:19], v194 offset:0x4800
	ds_read_b64_tr_b16 v[20:21], v194 offset:0x5000
	ds_read_b64_tr_b16 v[22:23], v194 offset:0x5800
	ds_read_b64_tr_b16 v[24:25], v194 offset:0x6000
	ds_read_b64_tr_b16 v[26:27], v194 offset:0x6800
	ds_read_b64_tr_b16 v[28:29], v194 offset:0x7000
	ds_read_b64_tr_b16 v[30:31], v194 offset:0x7800
	s_waitcnt lgkmcnt(0)
	s_nop 0
	v_mfma_f32_32x32x16_bf16 v[0:15], v[184:187], v[16:19], v[64:79]
	ds_read_b64_tr_b16 v[32:33], v194 offset:0x4200
	ds_read_b64_tr_b16 v[34:35], v194 offset:0x4a00
	ds_read_b64_tr_b16 v[36:37], v194 offset:0x5200
	ds_read_b64_tr_b16 v[38:39], v194 offset:0x5a00
	ds_read_b64_tr_b16 v[40:41], v194 offset:0x6200
	ds_read_b64_tr_b16 v[42:43], v194 offset:0x6a00
	ds_read_b64_tr_b16 v[44:45], v194 offset:0x7200
	v_mfma_f32_32x32x16_bf16 v[0:15], v[180:183], v[20:23], v[0:15]
	ds_read_b64_tr_b16 v[46:47], v194 offset:0x7a00
	v_mfma_f32_32x32x16_bf16 v[0:15], v[172:175], v[24:27], v[0:15]
	v_mfma_f32_32x32x16_bf16 v[0:15], v[176:179], v[28:31], v[0:15]
	s_waitcnt lgkmcnt(0)
	v_mfma_f32_32x32x16_bf16 v[16:31], v[184:187], v[32:35], v[80:95]
	ds_read_b64_tr_b16 v[48:49], v194 offset:0x4400
	ds_read_b64_tr_b16 v[50:51], v194 offset:0x4c00
	ds_read_b64_tr_b16 v[52:53], v194 offset:0x5400
	ds_read_b64_tr_b16 v[54:55], v194 offset:0x5c00
	ds_read_b64_tr_b16 v[56:57], v194 offset:0x6400
	ds_read_b64_tr_b16 v[58:59], v194 offset:0x6c00
	ds_read_b64_tr_b16 v[60:61], v194 offset:0x7400
	v_mfma_f32_32x32x16_bf16 v[16:31], v[180:183], v[36:39], v[16:31]
	ds_read_b64_tr_b16 v[62:63], v194 offset:0x7c00
	s_and_b64 s[4:5], s[46:47], exec
	s_cselect_b32 s4, s89, s53
	s_lshl_b32 s4, s4, 6
	s_cmp_le_i32 s4, s86
	s_cselect_b64 vcc, -1, 0
	v_cndmask_b32_e32 v78, v204, v130, vcc
	v_cndmask_b32_e32 v77, v204, v131, vcc
	v_cndmask_b32_e32 v74, v204, v134, vcc
	v_cndmask_b32_e32 v73, v204, v135, vcc
	v_max_f32_e32 v64, v77, v77
	v_max_f32_e32 v81, v78, v78
	v_cndmask_b32_e32 v72, v204, v136, vcc
	v_cndmask_b32_e32 v71, v204, v137, vcc
	v_max_f32_e32 v64, v81, v64
	v_max_f32_e32 v81, v73, v73
	v_max_f32_e32 v82, v74, v74
	v_cndmask_b32_e32 v70, v204, v138, vcc
	v_cndmask_b32_e32 v69, v204, v139, vcc
	v_max_f32_e32 v81, v82, v81
	v_mfma_f32_32x32x16_bf16 v[16:31], v[172:175], v[40:43], v[16:31]
	v_max_f32_e32 v82, v71, v71
	v_max_f32_e32 v83, v72, v72
	v_cndmask_b32_e32 v66, v204, v142, vcc
	v_cndmask_b32_e32 v65, v204, v143, vcc
	v_max_f32_e32 v82, v83, v82
	v_max_f32_e32 v83, v69, v69
	v_max_f32_e32 v84, v70, v70
	v_max_f32_e32 v83, v84, v83
	v_max_f32_e32 v84, v65, v65
	v_max_f32_e32 v85, v66, v66
	v_cndmask_b32_e32 v68, v204, v140, vcc
	v_cndmask_b32_e32 v67, v204, v141, vcc
	v_max_f32_e32 v84, v85, v84
	v_cndmask_b32_e32 v76, v204, v132, vcc
	v_cndmask_b32_e32 v75, v204, v133, vcc
	v_mfma_f32_32x32x16_bf16 v[16:31], v[176:179], v[44:47], v[16:31]
	v_cndmask_b32_e32 v80, v204, v128, vcc
	v_cndmask_b32_e32 v79, v204, v129, vcc
	v_max3_f32 v84, v68, v67, v84
	v_max3_f32 v64, v80, v79, v64
	v_max3_f32 v81, v76, v75, v81
	v_max3_f32 v82, v82, v83, v84
	v_max3_f32 v64, v64, v81, v82
	v_mov_b32_e32 v81, v64
	s_nop 1
	v_permlane32_swap_b32_e32 v64, v81
	v_max_f32_e32 v81, v81, v81
	v_max_f32_e32 v64, v64, v64
	v_max_f32_e32 v64, v64, v81
	s_waitcnt lgkmcnt(0)
	v_mfma_f32_32x32x16_bf16 v[32:47], v[184:187], v[48:51], v[96:111]
	ds_read_b64_tr_b16 v[234:235], v194 offset:0x4600
	ds_read_b64_tr_b16 v[236:237], v194 offset:0x4e00
	ds_read_b64_tr_b16 v[238:239], v194 offset:0x5600
	ds_read_b64_tr_b16 v[240:241], v194 offset:0x5e00
	ds_read_b64_tr_b16 v[242:243], v194 offset:0x6600
	ds_read_b64_tr_b16 v[244:245], v194 offset:0x6e00
	ds_read_b64_tr_b16 v[246:247], v194 offset:0x7600
	s_and_saveexec_b64 s[4:5], s[2:3]
	ds_write_b32 v226, v64 offset:1024
	s_or_b64 exec, exec, s[4:5]
	v_cndmask_b32_e64 v81, 0, 1, s[50:51]
	v_cmp_ne_u32_e64 s[4:5], 1, v81
	s_andn2_b64 vcc, exec, s[50:51]
	s_cbranch_vccnz .Lm0_h2B_398
	s_waitcnt vmcnt(1)
	ds_write_b128 v228, v[148:151]
	s_waitcnt vmcnt(0)
	ds_write_b128 v228, v[152:155] offset:8192
; template <int VB, bool SK>
; __device__ __forceinline__ void pv_tile(f32x16* o, int vb0, bf16x8 pa0, bf16x8 pa1, bf16x8 pa2, bf16x8 pa3, bool act) {
;     if (SK && !act) return;
;     ...
;     PV_D0(0); PV_D0(1); PV_D0(2); PV_D0(3);
.Lm0_h2B_398:
	v_mfma_f32_32x32x16_bf16 v[32:47], v[180:183], v[52:55], v[32:47]
	ds_read_b64_tr_b16 v[248:249], v194 offset:0x7e00
	s_waitcnt vmcnt(3)
	ds_write_b128 v216, v[156:159] offset:32768
	s_waitcnt vmcnt(2)
	ds_write_b128 v217, v[160:163] offset:32768
	s_waitcnt vmcnt(1)
	ds_write_b128 v216, v[164:167] offset:49152
	s_waitcnt vmcnt(0)
	ds_write_b128 v217, v[168:171] offset:49152
	v_mfma_f32_32x32x16_bf16 v[32:47], v[172:175], v[56:59], v[32:47]
	s_cmp_gt_u32 s87, s85
	s_cbranch_scc1 .Lm0_h2B_400
	s_add_i32 s38, s53, -2
	s_and_b64 s[50:51], s[46:47], exec
	s_cselect_b32 s38, s87, s38
	s_lshl_b32 s38, s38, 6
	s_lshl_b64 s[50:51], s[38:39], 8
	s_or_b32 s38, s38, 32
	v_lshl_add_u64 v[82:83], v[198:199], 0, s[50:51]
	s_lshl_b64 s[50:51], s[38:39], 8
	v_lshl_add_u64 v[84:85], v[198:199], 0, s[50:51]
	global_load_dwordx4 v[148:151], v[82:83], off
	global_load_dwordx4 v[152:155], v[84:85], off
.Lm0_h2B_400:
	v_mfma_f32_32x32x16_bf16 v[32:47], v[176:179], v[60:63], v[32:47]
	s_and_b64 vcc, exec, s[4:5]
	s_cbranch_vccnz .Lm0_h2B_367
	s_add_i32 s38, s53, -1
	s_and_b64 s[4:5], s[46:47], exec
	s_cselect_b32 s4, s88, s38
	s_lshl_b32 s38, s4, 6
	s_lshl_b64 s[4:5], s[38:39], 8
	s_or_b32 s38, s38, 32
	v_lshl_add_u64 v[82:83], v[200:201], 0, s[4:5]
	s_lshl_b64 s[50:51], s[38:39], 8
	v_lshl_add_u64 v[84:85], v[200:201], 0, s[50:51]
	global_load_dwordx4 v[156:159], v[82:83], off
	global_load_dwordx4 v[160:163], v[84:85], off
	v_lshl_add_u64 v[82:83], v[202:203], 0, s[4:5]
	v_lshl_add_u64 v[84:85], v[202:203], 0, s[50:51]
	global_load_dwordx4 v[164:167], v[82:83], off
	global_load_dwordx4 v[168:171], v[84:85], off
	s_branch .Lm0_h2B_367
.Lm0_h2B_367:
	s_waitcnt lgkmcnt(0)
	v_mfma_f32_32x32x16_bf16 v[48:63], v[184:187], v[234:237], v[112:127]
	v_add_f32_e32 v90, v231, v232
	v_fmac_f32_e32 v90, v227, v229
	v_mul_f32_e32 v89, 0xbe0293ee, v218
	v_fmamk_f32 v80, v80, 0x3e0293ee, v89
	v_fmamk_f32 v79, v79, 0x3e0293ee, v89
	v_fmamk_f32 v78, v78, 0x3e0293ee, v89
	v_fmamk_f32 v77, v77, 0x3e0293ee, v89
	v_fmamk_f32 v72, v72, 0x3e0293ee, v89
	v_fmamk_f32 v71, v71, 0x3e0293ee, v89
	v_fmamk_f32 v70, v70, 0x3e0293ee, v89
	v_fmamk_f32 v69, v69, 0x3e0293ee, v89
	v_exp_f32_e32 v80, v80
	v_exp_f32_e32 v82, v79
	v_exp_f32_e32 v78, v78
	v_exp_f32_e32 v84, v77
	v_mfma_f32_32x32x16_bf16 v[48:63], v[180:183], v[238:241], v[48:63]
	v_fmamk_f32 v76, v76, 0x3e0293ee, v89
	v_fmamk_f32 v75, v75, 0x3e0293ee, v89
	v_fmamk_f32 v74, v74, 0x3e0293ee, v89
	v_fmamk_f32 v73, v73, 0x3e0293ee, v89
	v_exp_f32_e32 v81, v72
	v_exp_f32_e32 v83, v71
	v_exp_f32_e32 v79, v70
	v_exp_f32_e32 v85, v69
	v_mfma_f32_32x32x16_bf16 v[48:63], v[172:175], v[242:245], v[48:63]
	v_fmamk_f32 v68, v68, 0x3e0293ee, v89
	v_fmamk_f32 v67, v67, 0x3e0293ee, v89
	v_fmamk_f32 v66, v66, 0x3e0293ee, v89
	v_fmac_f32_e32 v89, 0x3e0293ee, v65
	v_exp_f32_e32 v76, v76
	v_exp_f32_e32 v86, v75
	v_exp_f32_e32 v74, v74
	v_exp_f32_e32 v88, v73
	v_mfma_f32_32x32x16_bf16 v[48:63], v[176:179], v[246:249], v[48:63]
	v_exp_f32_e32 v77, v68
	v_exp_f32_e32 v87, v67
	v_exp_f32_e32 v75, v66
	v_exp_f32_e32 v89, v89
	v_pk_add_f32 v[66:67], v[80:81], v[82:83]
	v_pk_add_f32 v[68:69], v[78:79], v[84:85]
	v_pk_add_f32 v[70:71], v[74:75], v[88:89]
	v_pk_add_f32 v[66:67], v[66:67], v[68:69]
	v_pk_add_f32 v[68:69], v[76:77], v[86:87]
	s_nop 0
	v_pk_add_f32 v[68:69], v[68:69], v[70:71]
	s_nop 0
	v_pk_add_f32 v[66:67], v[66:67], v[68:69]
	s_nop 0
	v_pk_add_f32 v[66:67], v[66:67], v[66:67] op_sel:[0,1] op_sel_hi:[1,0]
	s_nop 0
	v_mov_b32_e32 v65, v66
	s_nop 1
	v_permlane32_swap_b32_e32 v66, v65
	v_add_f32_e32 v227, v66, v65
	v_fmac_f32_e32 v227, v90, v230
	v_cvt_pk_bf16_f32 v172, v80, v82
	v_cvt_pk_bf16_f32 v173, v78, v84
	v_cvt_pk_bf16_f32 v174, v76, v86
	v_cvt_pk_bf16_f32 v175, v74, v88
	v_cvt_pk_bf16_f32 v176, v81, v83
	v_cvt_pk_bf16_f32 v177, v79, v85
	v_cvt_pk_bf16_f32 v178, v77, v87
	v_cvt_pk_bf16_f32 v179, v75, v89
	s_nop 0
	v_permlane32_swap_b32_e32 v172, v174
	v_permlane32_swap_b32_e32 v173, v175
	v_permlane32_swap_b32_e32 v176, v178
	v_permlane32_swap_b32_e32 v177, v179
	ds_write_b128 v219, v[172:175] offset:16384
	ds_write_b128 v219, v[176:179] offset:17408
	s_mov_b64 s[4:5], 0
.LBB0_388:
	s_andn2_b64 vcc, exec, s[4:5]
	s_cbranch_vccnz .LBB0_390
	ds_read_b64_tr_b16 v[16:17], v194 offset:0
	ds_read_b64_tr_b16 v[18:19], v194 offset:0x800
	ds_read_b64_tr_b16 v[20:21], v194 offset:0x1000
	ds_read_b64_tr_b16 v[22:23], v194 offset:0x1800
	ds_read_b64_tr_b16 v[24:25], v194 offset:0x2000
	ds_read_b64_tr_b16 v[26:27], v194 offset:0x2800
	ds_read_b64_tr_b16 v[28:29], v194 offset:0x3000
	ds_read_b64_tr_b16 v[30:31], v194 offset:0x3800
	s_waitcnt lgkmcnt(0)
	s_nop 0
	v_mfma_f32_32x32x16_bf16 v[0:15], v[172:175], v[16:19], v[64:79]
	ds_read_b64_tr_b16 v[32:33], v194 offset:0x200
	ds_read_b64_tr_b16 v[34:35], v194 offset:0xa00
	ds_read_b64_tr_b16 v[36:37], v194 offset:0x1200
	ds_read_b64_tr_b16 v[38:39], v194 offset:0x1a00
	ds_read_b64_tr_b16 v[40:41], v194 offset:0x2200
	ds_read_b64_tr_b16 v[42:43], v194 offset:0x2a00
	ds_read_b64_tr_b16 v[44:45], v194 offset:0x3200
	v_mfma_f32_32x32x16_bf16 v[0:15], v[176:179], v[20:23], v[0:15]
	ds_read_b64_tr_b16 v[46:47], v194 offset:0x3a00
	v_mfma_f32_32x32x16_bf16 v[0:15], v[184:187], v[24:27], v[0:15]
	v_mfma_f32_32x32x16_bf16 v[0:15], v[180:183], v[28:31], v[0:15]
	s_waitcnt lgkmcnt(0)
; template <int VB, bool SK>
; __device__ __forceinline__ void pv_tile(f32x16* o, int vb0, bf16x8 pa0, bf16x8 pa1, bf16x8 pa2, bf16x8 pa3, bool act) {
;     if (SK && !act) return;
;     ...
;     PV_D0(0); PV_D0(1); PV_D0(2); PV_D0(3);
	v_mfma_f32_32x32x16_bf16 v[16:31], v[172:175], v[32:35], v[80:95]
	ds_read_b64_tr_b16 v[48:49], v194 offset:0x400
	ds_read_b64_tr_b16 v[50:51], v194 offset:0xc00
	ds_read_b64_tr_b16 v[52:53], v194 offset:0x1400
	ds_read_b64_tr_b16 v[54:55], v194 offset:0x1c00
	ds_read_b64_tr_b16 v[56:57], v194 offset:0x2400
	ds_read_b64_tr_b16 v[58:59], v194 offset:0x2c00
	ds_read_b64_tr_b16 v[60:61], v194 offset:0x3400
	v_mfma_f32_32x32x16_bf16 v[16:31], v[176:179], v[36:39], v[16:31]
	ds_read_b64_tr_b16 v[62:63], v194 offset:0x3c00
	s_and_b64 s[4:5], s[46:47], exec
	s_cselect_b32 s4, s89, s53
	s_lshl_b32 s4, s4, 6
	s_cmp_le_i32 s4, s86
	s_cselect_b64 vcc, -1, 0
	v_cndmask_b32_e32 v78, v204, v130, vcc
	v_cndmask_b32_e32 v77, v204, v131, vcc
	v_cndmask_b32_e32 v74, v204, v134, vcc
	v_cndmask_b32_e32 v73, v204, v135, vcc
	v_max_f32_e32 v64, v77, v77
	v_max_f32_e32 v81, v78, v78
	v_cndmask_b32_e32 v72, v204, v136, vcc
	v_cndmask_b32_e32 v71, v204, v137, vcc
	v_max_f32_e32 v64, v81, v64
	v_max_f32_e32 v81, v73, v73
	v_max_f32_e32 v82, v74, v74
	v_cndmask_b32_e32 v70, v204, v138, vcc
	v_cndmask_b32_e32 v69, v204, v139, vcc
	v_max_f32_e32 v81, v82, v81
	v_mfma_f32_32x32x16_bf16 v[16:31], v[184:187], v[40:43], v[16:31]
	v_max_f32_e32 v82, v71, v71
	v_max_f32_e32 v83, v72, v72
	v_cndmask_b32_e32 v66, v204, v142, vcc
	v_cndmask_b32_e32 v65, v204, v143, vcc
	v_max_f32_e32 v82, v83, v82
	v_max_f32_e32 v83, v69, v69
	v_max_f32_e32 v84, v70, v70
	v_max_f32_e32 v83, v84, v83
	v_max_f32_e32 v84, v65, v65
	v_max_f32_e32 v85, v66, v66
	v_cndmask_b32_e32 v68, v204, v140, vcc
	v_cndmask_b32_e32 v67, v204, v141, vcc
	v_max_f32_e32 v84, v85, v84
	v_cndmask_b32_e32 v76, v204, v132, vcc
	v_cndmask_b32_e32 v75, v204, v133, vcc
	v_mfma_f32_32x32x16_bf16 v[16:31], v[180:183], v[44:47], v[16:31]
	v_cndmask_b32_e32 v80, v204, v128, vcc
	v_cndmask_b32_e32 v79, v204, v129, vcc
	v_max3_f32 v84, v68, v67, v84
	v_max3_f32 v64, v80, v79, v64
	v_max3_f32 v81, v76, v75, v81
	v_max3_f32 v82, v82, v83, v84
	v_max3_f32 v64, v64, v81, v82
	v_mov_b32_e32 v81, v64
	s_nop 1
	v_permlane32_swap_b32_e32 v64, v81
	v_max_f32_e32 v81, v81, v81
	v_max_f32_e32 v64, v64, v64
	v_max_f32_e32 v64, v64, v81
	s_waitcnt lgkmcnt(0)
	v_mfma_f32_32x32x16_bf16 v[32:47], v[172:175], v[48:51], v[96:111]
	ds_read_b64_tr_b16 v[234:235], v194 offset:0x600
	ds_read_b64_tr_b16 v[236:237], v194 offset:0xe00
	ds_read_b64_tr_b16 v[238:239], v194 offset:0x1600
	ds_read_b64_tr_b16 v[240:241], v194 offset:0x1e00
	ds_read_b64_tr_b16 v[242:243], v194 offset:0x2600
	ds_read_b64_tr_b16 v[244:245], v194 offset:0x2e00
	ds_read_b64_tr_b16 v[246:247], v194 offset:0x3600
	s_and_saveexec_b64 s[4:5], s[2:3]
	ds_write_b32 v226, v64 offset:1024
	s_or_b64 exec, exec, s[4:5]
	v_cndmask_b32_e64 v81, 0, 1, s[50:51]
	v_cmp_ne_u32_e64 s[4:5], 1, v81
	s_andn2_b64 vcc, exec, s[50:51]
	s_cbranch_vccnz .Lm0_h2A_398
	s_waitcnt vmcnt(1)
	ds_write_b128 v228, v[148:151]
	s_waitcnt vmcnt(0)
	ds_write_b128 v228, v[152:155] offset:8192
.Lm0_h2A_398:
	v_mfma_f32_32x32x16_bf16 v[32:47], v[176:179], v[52:55], v[32:47]
	ds_read_b64_tr_b16 v[248:249], v194 offset:0x3e00
	s_waitcnt vmcnt(3)
	ds_write_b128 v216, v[156:159] offset:32768
	s_waitcnt vmcnt(2)
	ds_write_b128 v217, v[160:163] offset:32768
	s_waitcnt vmcnt(1)
	ds_write_b128 v216, v[164:167] offset:49152
	s_waitcnt vmcnt(0)
	ds_write_b128 v217, v[168:171] offset:49152
	v_mfma_f32_32x32x16_bf16 v[32:47], v[184:187], v[56:59], v[32:47]
	s_cmp_gt_u32 s87, s85
	s_cbranch_scc1 .Lm0_h2A_400
	s_add_i32 s38, s53, -2
	s_and_b64 s[50:51], s[46:47], exec
	s_cselect_b32 s38, s87, s38
	s_lshl_b32 s38, s38, 6
	s_lshl_b64 s[50:51], s[38:39], 8
	s_or_b32 s38, s38, 32
	v_lshl_add_u64 v[82:83], v[198:199], 0, s[50:51]
	s_lshl_b64 s[50:51], s[38:39], 8
	v_lshl_add_u64 v[84:85], v[198:199], 0, s[50:51]
	global_load_dwordx4 v[148:151], v[82:83], off
	global_load_dwordx4 v[152:155], v[84:85], off
; template <int VB, bool SK>
; __device__ __forceinline__ void pv_tile(f32x16* o, int vb0, bf16x8 pa0, bf16x8 pa1, bf16x8 pa2, bf16x8 pa3, bool act) {
;     if (SK && !act) return;
;     ...
;     PV_D0(0); PV_D0(1); PV_D0(2); PV_D0(3);
.Lm0_h2A_400:
	v_mfma_f32_32x32x16_bf16 v[32:47], v[180:183], v[60:63], v[32:47]
	s_and_b64 vcc, exec, s[4:5]
	s_cbranch_vccnz .Lm0_h2A_367
	s_add_i32 s38, s53, -1
	s_and_b64 s[4:5], s[46:47], exec
	s_cselect_b32 s4, s88, s38
	s_lshl_b32 s38, s4, 6
	s_lshl_b64 s[4:5], s[38:39], 8
	s_or_b32 s38, s38, 32
	v_lshl_add_u64 v[82:83], v[200:201], 0, s[4:5]
	s_lshl_b64 s[50:51], s[38:39], 8
	v_lshl_add_u64 v[84:85], v[200:201], 0, s[50:51]
	global_load_dwordx4 v[156:159], v[82:83], off
	global_load_dwordx4 v[160:163], v[84:85], off
	v_lshl_add_u64 v[82:83], v[202:203], 0, s[4:5]
	v_lshl_add_u64 v[84:85], v[202:203], 0, s[50:51]
	global_load_dwordx4 v[164:167], v[82:83], off
	global_load_dwordx4 v[168:171], v[84:85], off
	s_branch .Lm0_h2A_367
.Lm0_h2A_367:
	s_waitcnt lgkmcnt(0)
	v_mfma_f32_32x32x16_bf16 v[48:63], v[172:175], v[234:237], v[112:127]
	v_add_f32_e32 v90, v231, v232
	v_fmac_f32_e32 v90, v227, v229
	v_mul_f32_e32 v89, 0xbe0293ee, v218
	v_fmamk_f32 v80, v80, 0x3e0293ee, v89
	v_fmamk_f32 v79, v79, 0x3e0293ee, v89
	v_fmamk_f32 v78, v78, 0x3e0293ee, v89
	v_fmamk_f32 v77, v77, 0x3e0293ee, v89
	v_fmamk_f32 v72, v72, 0x3e0293ee, v89
	v_fmamk_f32 v71, v71, 0x3e0293ee, v89
	v_fmamk_f32 v70, v70, 0x3e0293ee, v89
	v_fmamk_f32 v69, v69, 0x3e0293ee, v89
	v_exp_f32_e32 v80, v80
	v_exp_f32_e32 v82, v79
	v_exp_f32_e32 v78, v78
	v_exp_f32_e32 v84, v77
	v_mfma_f32_32x32x16_bf16 v[48:63], v[176:179], v[238:241], v[48:63]
	v_fmamk_f32 v76, v76, 0x3e0293ee, v89
	v_fmamk_f32 v75, v75, 0x3e0293ee, v89
	v_fmamk_f32 v74, v74, 0x3e0293ee, v89
	v_fmamk_f32 v73, v73, 0x3e0293ee, v89
	v_exp_f32_e32 v81, v72
	v_exp_f32_e32 v83, v71
	v_exp_f32_e32 v79, v70
	v_exp_f32_e32 v85, v69
	v_mfma_f32_32x32x16_bf16 v[48:63], v[184:187], v[242:245], v[48:63]
	v_fmamk_f32 v68, v68, 0x3e0293ee, v89
	v_fmamk_f32 v67, v67, 0x3e0293ee, v89
	v_fmamk_f32 v66, v66, 0x3e0293ee, v89
	v_fmac_f32_e32 v89, 0x3e0293ee, v65
	v_exp_f32_e32 v76, v76
	v_exp_f32_e32 v86, v75
	v_exp_f32_e32 v74, v74
	v_exp_f32_e32 v88, v73
	v_mfma_f32_32x32x16_bf16 v[48:63], v[180:183], v[246:249], v[48:63]
	v_exp_f32_e32 v77, v68
	v_exp_f32_e32 v87, v67
	v_exp_f32_e32 v75, v66
	v_exp_f32_e32 v89, v89
	v_pk_add_f32 v[66:67], v[80:81], v[82:83]
	v_pk_add_f32 v[68:69], v[78:79], v[84:85]
	v_pk_add_f32 v[70:71], v[74:75], v[88:89]
	v_pk_add_f32 v[66:67], v[66:67], v[68:69]
	v_pk_add_f32 v[68:69], v[76:77], v[86:87]
	s_nop 0
	v_pk_add_f32 v[68:69], v[68:69], v[70:71]
	s_nop 0
	v_pk_add_f32 v[66:67], v[66:67], v[68:69]
	s_nop 0
	v_pk_add_f32 v[66:67], v[66:67], v[66:67] op_sel:[0,1] op_sel_hi:[1,0]
	s_nop 0
	v_mov_b32_e32 v65, v66
	s_nop 1
	v_permlane32_swap_b32_e32 v66, v65
	v_add_f32_e32 v227, v66, v65
	v_fmac_f32_e32 v227, v90, v230
	v_cvt_pk_bf16_f32 v172, v80, v82
	v_cvt_pk_bf16_f32 v173, v78, v84
	v_cvt_pk_bf16_f32 v174, v76, v86
	v_cvt_pk_bf16_f32 v175, v74, v88
	v_cvt_pk_bf16_f32 v176, v81, v83
	v_cvt_pk_bf16_f32 v177, v79, v85
	v_cvt_pk_bf16_f32 v178, v77, v87
	v_cvt_pk_bf16_f32 v179, v75, v89
	s_nop 0
	v_permlane32_swap_b32_e32 v172, v174
	v_permlane32_swap_b32_e32 v173, v175
	v_permlane32_swap_b32_e32 v176, v178
	v_permlane32_swap_b32_e32 v177, v179
	ds_write_b128 v219, v[172:175] offset:16384
	ds_write_b128 v219, v[176:179] offset:17408

; #define SBAR() __builtin_amdgcn_sched_barrier(0)
; __device__ __forceinline__ void attn2_block(const Block2& B, char* lds) {
;     ...
;     float m_cur, mn_p, alpha_p = 1.f, pmax_own;
;     qkt_half<0>(p, K_lds, r32, hi, kh, qf, q0); SBAR(); A3_MASKMAX(0, 0);
;     __syncthreads();
;     m_cur = fmaxf(fmaxf(pmax_own, xm[(wid ^ 4) * 32 + r32]), -1e30f); mn_p = m_cur;
;     for (int t = 0; t < NT; t += 2) { A3_STEP(t, 0); A3_STEP(t + 1, 1); }
.LBB0_394:
	s_branch .LBB0_367
